# per-wave-buffer_inv-after-closing-barrier
# baseline (speedup 1.0000x reference)
.LBB0_226:
	s_or_b64 exec, exec, s[4:5]
	s_mov_b64 s[4:5], 0
	s_waitcnt lgkmcnt(0)
	s_barrier
	buffer_inv sc1

.LBB0_591:
	s_or_b64 exec, exec, s[0:1]
	s_mov_b64 s[0:1], 0
	s_waitcnt lgkmcnt(0)
	s_barrier
	buffer_inv sc1

.Lsbar_acq:
	s_cmp_eq_u32 s98, 1
	s_cbranch_scc1 .LBB0_226
	s_cmp_eq_u32 s98, 2
	s_cbranch_scc1 .LBB0_411
	s_cmp_eq_u32 s98, 3
	s_cbranch_scc1 .LBB0_514
	s_cmp_eq_u32 s98, 4
	s_cbranch_scc1 .LBB0_591
	s_cmp_eq_u32 s98, 5
	s_cbranch_scc1 .LBB0_672
	s_cmp_eq_u32 s98, 6
	s_cbranch_scc1 .LBB0_775
	s_cmp_eq_u32 s98, 7
	s_cbranch_scc1 .LBB0_846
	s_cmp_eq_u32 s98, 8
	s_cbranch_scc1 .LBB0_1096
	s_cmp_eq_u32 s98, 9
	s_cbranch_scc1 .LBB0_1229
	s_cmp_eq_u32 s98, 10
	s_cbranch_scc1 .LBB0_1332
	s_cmp_eq_u32 s98, 11
	s_cbranch_scc1 .LBB0_1403
	s_cmp_eq_u32 s98, 12
	s_cbranch_scc1 .LBB0_1484
	s_branch .LBB0_1588

.LBB0_1588:
	s_or_b64 exec, exec, s[2:3]
	s_mov_b64 s[2:3], 0
	s_waitcnt lgkmcnt(0)
	s_barrier
	buffer_inv sc1
